# attention riding on the scan staging waves: next key tile K fragments prefetched at the end of each tile
# speedup vs baseline: 1.0305x; 1.0113x over previous
; __device__ __forceinline__ void scan_phase(const Ctx& F, const float* sbg) {
;     ...
;             const int ht = F.tid - 256, stp = ht >> 3, col8 = (ht & 7) * 8;
;             const unsigned char* sbase = F.ws + WS_SCAN + ((size_t)bh * SEQ * 64) * 2 + (size_t)ht * 16;
;             const float* scal = (const float*)(F.ws + WS_SCAL) + (size_t)bh * SEQ * 2;
;             u32x4 st[6]; float krv = 0.f;
;             int au = (unit == (int)F.bid) ? (F.bid * 4 + (F.wave - 4)) : 64 * 128, akt = -1; bf16x8 aqf[4]; f32x16 ao0, ao1; float acarry = 0.f;
.LBB0_662:
	s_and_b32 s93, s33, 3
	s_mov_b64 s[0:1], -1
	s_and_b64 vcc, exec, s[60:61]
	s_waitcnt vmcnt(0)
	s_barrier
	s_cbranch_vccz .LBB0_691
	s_ashr_i32 s24, s33, 2
	s_and_b32 s0, s77, 3
	s_ashr_i32 s25, s24, 31
	s_lshl_b32 s27, s0, 6
	s_lshl_b64 s[0:1], s[24:25], 20
	v_readlane_b32 s22, v253, 53
	s_add_u32 s28, s22, s0
	v_readlane_b32 s22, v253, 54
	s_addc_u32 s29, s22, s1
	s_lshl_b64 s[22:23], s[24:25], 19
	v_lshl_add_u64 v[16:17], v[166:167], 0, s[22:23]
	s_mov_b32 s26, 0x2001000
	global_load_dwordx4 v[8:11], v[16:17], off
	v_add_co_u32_e32 v56, vcc, s26, v16
	s_mov_b32 s26, 0x4001000
	s_nop 0
	v_addc_co_u32_e32 v57, vcc, 0, v17, vcc
	global_load_dwordx4 v[12:15], v[56:57], off offset:-4096
	v_add_co_u32_e32 v62, vcc, s26, v16
	s_mov_b32 s30, 0x6001000
	s_nop 0
	v_addc_co_u32_e32 v63, vcc, 0, v17, vcc
	global_load_dwordx4 v[4:7], v[62:63], off offset:-4096
	v_add_co_u32_e32 v64, vcc, s30, v16
	s_movk_i32 s31, 0x1000
	s_nop 0
	v_addc_co_u32_e32 v65, vcc, 0, v17, vcc
	s_lshl_b64 s[24:25], s[24:25], 15
	v_readlane_b32 s30, v253, 56
	global_load_dwordx4 v[50:53], v[64:65], off offset:-4096
	s_add_u32 s86, s30, s24
	v_readlane_b32 s24, v253, 57
	v_add_co_u32_e32 v60, vcc, s31, v16
	s_mov_b32 s34, 0x8001000
	s_addc_u32 s87, s24, s25
	v_addc_co_u32_e32 v61, vcc, 0, v17, vcc
	v_lshl_add_u64 v[58:59], v[168:169], 2, s[86:87]
	v_add_co_u32_e32 v66, vcc, s34, v16
	global_load_dword v55, v[58:59], off
	s_nop 0
	v_addc_co_u32_e32 v67, vcc, 0, v17, vcc
	global_load_dwordx4 v[130:133], v[60:61], off
	global_load_dword v147, v[58:59], off offset:256
	s_mov_b32 s35, 0xa001000
	global_load_dwordx4 v[58:61], v[66:67], off offset:-4096
	v_add_co_u32_e32 v16, vcc, s35, v16
	global_load_dwordx4 v[134:137], v[56:57], off
	global_load_dwordx4 v[138:141], v[62:63], off
	v_addc_co_u32_e32 v17, vcc, 0, v17, vcc
	global_load_dwordx4 v[142:145], v[64:65], off
	s_nop 0
	global_load_dwordx4 v[62:65], v[16:17], off offset:-4096
	global_load_dwordx4 v[150:153], v[66:67], off
	global_load_dwordx4 v[154:157], v[16:17], off
	s_cmp_eq_u32 s33, s80
	v_readlane_b32 s24, v253, 55
	s_cselect_b32 s92, s24, 0x2000
	s_lshl_b32 s24, s93, 6
	s_add_u32 s24, s28, s24
	s_addc_u32 s25, s29, 0
	v_mov_b32_e32 v185, v3
	s_or_b32 s0, s0, s27
	v_mov_b64_e32 v[116:117], v[100:101]
	v_mov_b64_e32 v[120:121], v[104:105]
	v_mov_b64_e32 v[124:125], v[108:109]
	v_mov_b64_e32 v[128:129], v[112:113]
	s_mov_b32 s26, 0
	v_lshl_add_u64 v[186:187], s[24:25], 0, v[184:185]
	v_lshl_add_u64 v[188:189], v[180:181], 0, s[0:1]
	v_lshl_add_u64 v[190:191], v[182:183], 0, s[22:23]
	v_mov_b32_e32 v185, 0
	s_mov_b32 s81, -1
	s_movk_i32 s96, 0xfe00
	s_mov_b64 s[88:89], 0
	v_mov_b32_e32 v192, v209
	v_mov_b32_e32 v194, v208
	v_mov_b64_e32 v[114:115], v[98:99]
	v_mov_b64_e32 v[118:119], v[102:103]
	v_mov_b64_e32 v[122:123], v[106:107]
	v_mov_b64_e32 v[126:127], v[110:111]
	s_waitcnt vmcnt(13)
	v_cvt_f32_f16_e32 v66, v8
	v_cvt_f32_f16_sdwa v67, v8 dst_sel:DWORD dst_unused:UNUSED_PAD src0_sel:WORD_1
	v_cvt_f32_f16_e32 v68, v9
	v_cvt_f32_f16_sdwa v69, v9 dst_sel:DWORD dst_unused:UNUSED_PAD src0_sel:WORD_1
	v_cvt_f32_f16_e32 v8, v10
	v_cvt_f32_f16_sdwa v9, v10 dst_sel:DWORD dst_unused:UNUSED_PAD src0_sel:WORD_1
	v_cvt_f32_f16_e32 v10, v11
	v_cvt_f32_f16_sdwa v11, v11 dst_sel:DWORD dst_unused:UNUSED_PAD src0_sel:WORD_1
	s_waitcnt vmcnt(12)
	v_lshlrev_b32_e32 v2, 13, v12
	v_lshlrev_b32_e32 v16, 13, v13
	v_bfe_u32 v13, v13, 16, 16
	v_bfe_u32 v12, v12, 16, 16
	v_lshlrev_b32_e32 v54, 13, v15
	v_and_b32_e32 v16, 0xfffe000, v16
	v_and_b32_e32 v2, 0xfffe000, v2
	v_lshlrev_b32_e32 v17, 13, v14
	v_bfe_u32 v15, v15, 16, 16
	v_bfe_u32 v14, v14, 16, 16
	v_lshl_add_u32 v12, v12, 13, v211
	v_lshl_add_u32 v13, v13, 13, v211
	v_and_b32_e32 v54, 0xfffe000, v54
	ds_write_b128 v199, v[66:69] offset:256
	ds_write_b128 v199, v[8:11] offset:272
	v_add_u32_e32 v2, 0x38000000, v2
	v_add_u32_e32 v8, 0x38000000, v16
	v_lshl_add_u32 v14, v14, 13, v211
	v_lshl_add_u32 v15, v15, 13, v211
	v_sub_f32_e32 v11, 1.0, v13
	v_sub_f32_e32 v9, 1.0, v12
	v_add_u32_e32 v12, 0x38000000, v54
	v_sub_f32_e32 v10, 1.0, v8
	v_sub_f32_e32 v8, 1.0, v2
	v_and_b32_e32 v17, 0xfffe000, v17
	ds_write_b128 v199, v[8:11] offset:512
	v_sub_f32_e32 v11, 1.0, v15
	v_sub_f32_e32 v9, 1.0, v14
	v_sub_f32_e32 v10, 1.0, v12
	s_waitcnt vmcnt(11)
	v_cvt_f32_f16_e32 v12, v4
	v_cvt_f32_f16_sdwa v13, v4 dst_sel:DWORD dst_unused:UNUSED_PAD src0_sel:WORD_1
	v_cvt_f32_f16_e32 v14, v5
	v_cvt_f32_f16_sdwa v15, v5 dst_sel:DWORD dst_unused:UNUSED_PAD src0_sel:WORD_1
	v_add_u32_e32 v16, 0x38000000, v17
	v_cvt_f32_f16_e32 v4, v6
	v_cvt_f32_f16_sdwa v5, v6 dst_sel:DWORD dst_unused:UNUSED_PAD src0_sel:WORD_1
	v_cvt_f32_f16_e32 v6, v7
	v_cvt_f32_f16_sdwa v7, v7 dst_sel:DWORD dst_unused:UNUSED_PAD src0_sel:WORD_1
	v_sub_f32_e32 v8, 1.0, v16
	ds_write_b128 v199, v[8:11] offset:528
	ds_write_b128 v199, v[12:15] offset:768
	ds_write_b128 v199, v[4:7] offset:784
	s_waitcnt vmcnt(10)
	v_cvt_f32_f16_e32 v4, v51
	v_cvt_f32_f16_sdwa v6, v51 dst_sel:DWORD dst_unused:UNUSED_PAD src0_sel:WORD_1
	v_cvt_f32_f16_e32 v8, v52
	v_cvt_f32_f16_sdwa v10, v52 dst_sel:DWORD dst_unused:UNUSED_PAD src0_sel:WORD_1
	v_cvt_f32_f16_e32 v12, v53
	v_cvt_f32_f16_sdwa v14, v53 dst_sel:DWORD dst_unused:UNUSED_PAD src0_sel:WORD_1
	s_waitcnt vmcnt(9)
	v_mov_b32_e32 v5, v55
	v_mov_b32_e32 v7, v55
	v_cvt_f32_f16_e32 v54, v50
	v_cvt_f32_f16_sdwa v56, v50 dst_sel:DWORD dst_unused:UNUSED_PAD src0_sel:WORD_1
	ds_write_b128 v200, v[4:7] offset:1296
	v_mov_b32_e32 v9, v55
	v_mov_b32_e32 v11, v55
	s_waitcnt vmcnt(6)
; #define H_ISSUE(ch_) do { _Pragma("unroll") for (int a_ = 0; a_ < 6; ++a_) st[a_] = *(const u32x4*)(sbase + (size_t)a_ * SCAN_ARR + (size_t)(ch_) * (T * 64 * 2)); \
;         krv = scal[((ch_) * T + stp) * 2]; } while (0)
; __device__ __forceinline__ void attn_tile(const Ctx& F, int bh, int qt, int kt, const bf16x8 (&qf)[4], f32x16& o0, f32x16& o1, float& carry) {
;     ...
;     const unsigned ko = ((unsigned)b * SEQ + s0 + j) * 1024 + 512 + h * 64 + 8 * hi;
;     bf16x8 kf[4];
; #pragma unroll
;     for (int d0 = 0; d0 < 4; ++d0) kf[d0] = *(const bf16x8*)(QK + ko + d0 * 16);
; __device__ __forceinline__ void scan_phase(const Ctx& F, const float* sbg) {
;     ...
;             H_ISSUE(0); H_COMMIT(0); H_ISSUE(1);
;             __syncthreads();
	v_cvt_f32_f16_e32 v4, v58
	v_cvt_f32_f16_sdwa v5, v58 dst_sel:DWORD dst_unused:UNUSED_PAD src0_sel:WORD_1
	v_cvt_f32_f16_e32 v6, v59
	v_cvt_f32_f16_sdwa v7, v59 dst_sel:DWORD dst_unused:UNUSED_PAD src0_sel:WORD_1
	ds_write_b128 v200, v[8:11] offset:1312
	v_mov_b32_e32 v13, v55
	v_mov_b32_e32 v15, v55
	v_cvt_f32_f16_e32 v8, v60
	v_cvt_f32_f16_sdwa v9, v60 dst_sel:DWORD dst_unused:UNUSED_PAD src0_sel:WORD_1
	v_cvt_f32_f16_e32 v10, v61
	v_cvt_f32_f16_sdwa v11, v61 dst_sel:DWORD dst_unused:UNUSED_PAD src0_sel:WORD_1
	ds_write_b128 v200, v[12:15] offset:1328
	s_waitcnt vmcnt(2)
	v_cvt_f32_f16_e32 v12, v62
	v_cvt_f32_f16_sdwa v13, v62 dst_sel:DWORD dst_unused:UNUSED_PAD src0_sel:WORD_1
	v_cvt_f32_f16_e32 v14, v63
	v_cvt_f32_f16_sdwa v15, v63 dst_sel:DWORD dst_unused:UNUSED_PAD src0_sel:WORD_1
	v_mov_b32_e32 v57, v55
	v_cvt_f32_f16_e32 v50, v64
	v_cvt_f32_f16_sdwa v51, v64 dst_sel:DWORD dst_unused:UNUSED_PAD src0_sel:WORD_1
	v_cvt_f32_f16_e32 v52, v65
	v_cvt_f32_f16_sdwa v53, v65 dst_sel:DWORD dst_unused:UNUSED_PAD src0_sel:WORD_1
	ds_write_b128 v200, v[54:57] offset:1280
	ds_write_b128 v199, v[4:7]
	ds_write_b128 v199, v[8:11] offset:16
	ds_write_b128 v199, v[12:15] offset:1024
	ds_write_b128 v199, v[50:53] offset:1040
	v_mov_b64_e32 v[64:65], v[32:33]
	v_mov_b64_e32 v[80:81], v[48:49]
	v_mov_b64_e32 v[62:63], v[30:31]
	v_mov_b64_e32 v[60:61], v[28:29]
	v_mov_b64_e32 v[58:59], v[26:27]
	v_mov_b64_e32 v[56:57], v[24:25]
	v_mov_b64_e32 v[54:55], v[22:23]
	v_mov_b64_e32 v[52:53], v[20:21]
	v_mov_b64_e32 v[50:51], v[18:19]
	v_mov_b64_e32 v[78:79], v[46:47]
	v_mov_b64_e32 v[76:77], v[44:45]
	v_mov_b64_e32 v[74:75], v[42:43]
	v_mov_b64_e32 v[72:73], v[40:41]
	v_mov_b64_e32 v[70:71], v[38:39]
	v_mov_b64_e32 v[68:69], v[36:37]
	v_mov_b64_e32 v[66:67], v[34:35]
	s_mov_b32 s99, 0
	s_mov_b32 s101, 0
	v_mov_b32_e32 v220, s68
	v_mov_b32_e32 v221, s69
	global_load_dwordx4 v[82:85], v[220:221], off
	global_load_dwordx4 v[86:89], v[220:221], off offset:32
	global_load_dwordx4 v[90:93], v[220:221], off offset:64
	global_load_dwordx4 v[94:97], v[220:221], off offset:96
	s_waitcnt lgkmcnt(0)
	s_barrier
	s_add_i32 s94, s26, 1
	s_cmp_eq_u32 s88, 0x7f000
	s_cbranch_scc1 .LBB0_666
; #define H_ISSUE(ch_) do { _Pragma("unroll") for (int a_ = 0; a_ < 6; ++a_) st[a_] = *(const u32x4*)(sbase + (size_t)a_ * SCAN_ARR + (size_t)(ch_) * (T * 64 * 2)); \
;         krv = scal[((ch_) * T + stp) * 2]; } while (0)
; #define H_FLUSH(ch_) do { const LAS float* yb_ = ybufs + ((ch_) & 1) * (T * 16); \
;         _Pragma("unroll") for (int i_ = 0; i_ < 2; ++i_) { const int idx_ = ht + 256 * i_; Y[(size_t)((ch_) * T + (idx_ >> 4)) * 64 + qtr * 16 + (idx_ & 15)] = yb_[idx_]; } } while (0)
; __device__ __forceinline__ void scan_phase(const Ctx& F, const float* sbg) {
;     ...
;             H_ISSUE(0); H_COMMIT(0); H_ISSUE(1);
;             __syncthreads();
;             for (int ch = 0; ch < NCH; ++ch) {
;                 if (ch + 1 < NCH) { H_COMMIT((ch + 1) & 1); if (ch + 2 < NCH) H_ISSUE(ch + 2); }
;                 if (ch > 0) H_FLUSH(ch - 1);
.LBB0_664:
	s_waitcnt vmcnt(10)
	v_cvt_f32_f16_sdwa v5, v130 dst_sel:DWORD dst_unused:UNUSED_PAD src0_sel:WORD_1
	v_cvt_f32_f16_e32 v4, v130
	v_cvt_f32_f16_sdwa v7, v131 dst_sel:DWORD dst_unused:UNUSED_PAD src0_sel:WORD_1
	v_cvt_f32_f16_e32 v6, v131
	s_bitcmp1_b32 s94, 0
	v_cvt_f32_f16_sdwa v9, v132 dst_sel:DWORD dst_unused:UNUSED_PAD src0_sel:WORD_1
	v_cvt_f32_f16_e32 v8, v132
	v_cvt_f32_f16_sdwa v11, v133 dst_sel:DWORD dst_unused:UNUSED_PAD src0_sel:WORD_1
	v_cvt_f32_f16_e32 v10, v133
	s_cselect_b32 s0, 0xe000, 0
	v_add_u32_e32 v2, s0, v199
	ds_write_b128 v2, v[4:7] offset:256
	ds_write_b128 v2, v[8:11] offset:272
	s_waitcnt vmcnt(9)
	v_lshlrev_b32_e32 v4, 13, v134
	v_lshlrev_b32_e32 v5, 13, v135
	v_and_b32_e32 v5, 0xfffe000, v5
	v_and_b32_e32 v4, 0xfffe000, v4
	v_bfe_u32 v6, v135, 16, 16
	v_bfe_u32 v7, v134, 16, 16
	v_lshl_add_u32 v8, v7, 13, v211
	v_lshl_add_u32 v6, v6, 13, v211
	v_add_u32_e32 v4, 0x38000000, v4
	v_add_u32_e32 v9, 0x38000000, v5
	v_sub_f32_e32 v7, 1.0, v6
	v_sub_f32_e32 v5, 1.0, v8
	v_sub_f32_e32 v6, 1.0, v9
	v_sub_f32_e32 v4, 1.0, v4
	ds_write_b128 v2, v[4:7] offset:512
	v_lshlrev_b32_e32 v5, 13, v137
	v_and_b32_e32 v5, 0xfffe000, v5
	v_bfe_u32 v6, v137, 16, 16
	v_bfe_u32 v7, v136, 16, 16
	v_lshlrev_b32_e32 v4, 13, v136
	v_lshl_add_u32 v8, v7, 13, v211
	v_lshl_add_u32 v6, v6, 13, v211
	v_add_u32_e32 v9, 0x38000000, v5
	v_and_b32_e32 v4, 0xfffe000, v4
	v_sub_f32_e32 v7, 1.0, v6
	v_sub_f32_e32 v5, 1.0, v8
	v_sub_f32_e32 v6, 1.0, v9
	s_waitcnt vmcnt(8)
	v_cvt_f32_f16_sdwa v9, v138 dst_sel:DWORD dst_unused:UNUSED_PAD src0_sel:WORD_1
	v_cvt_f32_f16_e32 v8, v138
	v_cvt_f32_f16_sdwa v11, v139 dst_sel:DWORD dst_unused:UNUSED_PAD src0_sel:WORD_1
	v_cvt_f32_f16_e32 v10, v139
	v_add_u32_e32 v4, 0x38000000, v4
	v_cvt_f32_f16_sdwa v13, v140 dst_sel:DWORD dst_unused:UNUSED_PAD src0_sel:WORD_1
	v_cvt_f32_f16_e32 v12, v140
	v_cvt_f32_f16_sdwa v15, v141 dst_sel:DWORD dst_unused:UNUSED_PAD src0_sel:WORD_1
	v_cvt_f32_f16_e32 v14, v141
	v_sub_f32_e32 v4, 1.0, v4
	ds_write_b128 v2, v[4:7] offset:528
	ds_write_b128 v2, v[8:11] offset:768
	ds_write_b128 v2, v[12:15] offset:784
	s_waitcnt vmcnt(7)
	v_cvt_f32_f16_e32 v4, v143
	v_cvt_f32_f16_sdwa v6, v143 dst_sel:DWORD dst_unused:UNUSED_PAD src0_sel:WORD_1
	v_cvt_f32_f16_e32 v8, v144
	v_cvt_f32_f16_sdwa v10, v144 dst_sel:DWORD dst_unused:UNUSED_PAD src0_sel:WORD_1
	v_cvt_f32_f16_e32 v12, v145
	v_cvt_f32_f16_sdwa v14, v145 dst_sel:DWORD dst_unused:UNUSED_PAD src0_sel:WORD_1
	v_lshl_add_u32 v16, v165, 2, v2
	s_waitcnt vmcnt(4)
	v_mov_b32_e32 v5, v147
	v_mov_b32_e32 v7, v147
	ds_write_b128 v16, v[4:7] offset:1296
	s_waitcnt vmcnt(5)
	v_cvt_f32_f16_sdwa v5, v150 dst_sel:DWORD dst_unused:UNUSED_PAD src0_sel:WORD_1
	v_cvt_f32_f16_e32 v4, v150
	v_cvt_f32_f16_sdwa v7, v151 dst_sel:DWORD dst_unused:UNUSED_PAD src0_sel:WORD_1
	v_cvt_f32_f16_e32 v6, v151
	v_mov_b32_e32 v9, v147
	v_mov_b32_e32 v11, v147
	v_mov_b32_e32 v13, v147
	v_mov_b32_e32 v15, v147
	v_cvt_f32_f16_e32 v146, v142
	v_cvt_f32_f16_sdwa v148, v142 dst_sel:DWORD dst_unused:UNUSED_PAD src0_sel:WORD_1
	ds_write_b128 v16, v[8:11] offset:1312
	ds_write_b128 v16, v[12:15] offset:1328
	v_cvt_f32_f16_sdwa v9, v152 dst_sel:DWORD dst_unused:UNUSED_PAD src0_sel:WORD_1
	v_cvt_f32_f16_e32 v8, v152
	v_cvt_f32_f16_sdwa v11, v153 dst_sel:DWORD dst_unused:UNUSED_PAD src0_sel:WORD_1
	v_cvt_f32_f16_e32 v10, v153
	s_waitcnt vmcnt(4)
	v_cvt_f32_f16_sdwa v13, v156 dst_sel:DWORD dst_unused:UNUSED_PAD src0_sel:WORD_1
	v_cvt_f32_f16_e32 v12, v156
	v_cvt_f32_f16_sdwa v15, v157 dst_sel:DWORD dst_unused:UNUSED_PAD src0_sel:WORD_1
	v_cvt_f32_f16_e32 v14, v157
	ds_write_b128 v2, v[4:7]
	v_cvt_f32_f16_sdwa v5, v154 dst_sel:DWORD dst_unused:UNUSED_PAD src0_sel:WORD_1
	v_cvt_f32_f16_e32 v4, v154
	v_cvt_f32_f16_sdwa v7, v155 dst_sel:DWORD dst_unused:UNUSED_PAD src0_sel:WORD_1
	v_cvt_f32_f16_e32 v6, v155
	v_mov_b32_e32 v149, v147
	s_cmpk_gt_u32 s26, 0x7d
	ds_write_b128 v16, v[146:149] offset:1280
	ds_write_b128 v2, v[8:11] offset:16
	ds_write_b128 v2, v[4:7] offset:1024
	ds_write_b128 v2, v[12:15] offset:1040
	s_cbranch_scc1 .LBB0_666
	v_lshl_add_u64 v[4:5], v[190:191], 0, s[88:89]
	v_add_co_u32_e32 v6, vcc, 0x2c01000, v4
	v_mov_b32_e32 v193, v3
	s_nop 0
	v_addc_co_u32_e32 v7, vcc, 0, v5, vcc
	v_add_co_u32_e32 v8, vcc, 0x4c01000, v4
	s_nop 1
	v_addc_co_u32_e32 v9, vcc, 0, v5, vcc
	global_load_dwordx4 v[130:133], v[6:7], off
	global_load_dwordx4 v[134:137], v[8:9], off
	v_add_co_u32_e32 v6, vcc, 0x6c01000, v4
	s_nop 1
	v_addc_co_u32_e32 v7, vcc, 0, v5, vcc
	v_add_co_u32_e32 v8, vcc, 0x8c01000, v4
	s_nop 1
	v_addc_co_u32_e32 v9, vcc, 0, v5, vcc
	global_load_dwordx4 v[138:141], v[6:7], off
	global_load_dwordx4 v[142:145], v[8:9], off
	v_add_co_u32_e32 v6, vcc, 0xac01000, v4
	s_nop 1
	v_addc_co_u32_e32 v7, vcc, 0, v5, vcc
	v_add_co_u32_e32 v4, vcc, 0xcc01000, v4
	s_nop 1
	v_addc_co_u32_e32 v5, vcc, 0, v5, vcc
	global_load_dwordx4 v[150:153], v[6:7], off
	global_load_dwordx4 v[154:157], v[4:5], off
	v_lshl_add_u64 v[4:5], v[192:193], 2, s[86:87]
	global_load_dword v147, v[4:5], off
	s_add_i32 s101, s101, 7
.LBB0_666:
	s_cmp_eq_u32 s88, 0
	s_cbranch_scc1 .LBB0_668
	s_and_b32 s0, s96, 0x200
	s_lshl_b32 s0, s0, 2
	s_add_i32 s0, s0, 0
	s_add_i32 s0, s0, 0x1c000
	v_lshl_add_u32 v2, v164, 2, s0
	v_lshl_add_u32 v4, v163, 2, s0
	ds_read_b32 v2, v2
	ds_read_b32 v6, v4
	v_mov_b32_e32 v195, v3
	v_lshlrev_b64 v[4:5], 8, v[194:195]
	v_lshl_add_u64 v[4:5], v[186:187], 0, v[4:5]
	s_waitcnt lgkmcnt(1)
	global_store_dword v[188:189], v2, off
	s_waitcnt lgkmcnt(0)
	global_store_dword v[4:5], v6, off
	s_add_i32 s101, s101, 2

; #define MFMA32(a, b, c) __builtin_amdgcn_mfma_f32_32x32x16_f16(H8(a), H8(b), (c), 0, 0, 0)
; __device__ __forceinline__ void attn_tile(const Ctx& F, int bh, int qt, int kt, const bf16x8 (&qf)[4], f32x16& o0, f32x16& o1, float& carry) {
;     const int lane = F.lane, j = lane & 31, hi = lane >> 5; const int b = bh >> 3, h = bh & 7;
;     const bf16* QK = (const bf16*)(F.ws + WS_QK); const bf16* VT = (const bf16*)(F.ws + WS_VT);
;     const int s0 = kt * 32, qpos = qt * 32 + j;
;     const unsigned ko = ((unsigned)b * SEQ + s0 + j) * 1024 + 512 + h * 64 + 8 * hi;
;     bf16x8 kf[4];
; #pragma unroll
;     for (int d0 = 0; d0 < 4; ++d0) kf[d0] = *(const bf16x8*)(QK + ko + d0 * 16);
;     bf16x8 vf[2][2];
;     const unsigned vo = (unsigned)(h * 64 + j) * M + b * SEQ + s0 + 4 * hi;
; #pragma unroll
;     for (int dt = 0; dt < 2; ++dt)
; #pragma unroll
;         for (int s = 0; s < 2; ++s) { const bf16* vp = VT + vo + (unsigned)(dt * 32) * M + 16 * s;
;             const s16x4 lo = *(const s16x4*)vp, hh = *(const s16x4*)(vp + 8); vf[dt][s] = __builtin_shufflevector(lo, hh, 0, 1, 2, 3, 4, 5, 6, 7); }
;     f32x16 sT;
; #pragma unroll
;     for (int r = 0; r < 16; ++r) sT[r] = 0.f;
; #pragma unroll
;     for (int d0 = 0; d0 < 4; ++d0) sT = MFMA32(kf[d0], qf[d0], sT);
;     float lk[16], lz[16];
;     const bool diag = (kt == qt);
; #pragma unroll
;     for (int r = 0; r < 16; ++r) {
;         const float z = sT[r] * 0.125f;
;         const float sp = fmaxf(z, 0.f) + __logf(1.f + __expf(-fabsf(z)));
;         const int key = s0 + (r & 3) + 8 * (r >> 2) + 4 * hi;
;         const bool valid = !diag || (key < qpos);
.LBB0_673:
	s_cmp_eq_u32 s99, 1
	s_cbranch_scc1 .Lkpf_head
	s_and_b32 s0, s23, 0xfffff000
	s_or_b32 s1, s0, s24
	v_or_b32_e32 v2, s1, v170
	v_lshlrev_b32_e32 v2, 10, v2
	v_or3_b32 v2, v2, v202, s58
	v_or_b32_e32 v2, 0x200, v2
	v_lshl_add_u64 v[16:17], v[2:3], 1, s[68:69]
	global_load_dwordx4 v[4:7], v[16:17], off
	global_load_dwordx4 v[8:11], v[16:17], off offset:32
	global_load_dwordx4 v[12:15], v[16:17], off offset:64
	global_load_dwordx4 v[216:219], v[16:17], off offset:96
	v_or_b32_e32 v2, s58, v170
	v_or_b32_e32 v17, s24, v203
	v_lshlrev_b32_e32 v2, 15, v2
	v_add3_u32 v2, v2, s0, v17
	v_or_b32_e32 v146, s95, v170
	v_or_b32_e32 v16, 1, v17
	s_cmp_lg_u32 s81, s22
	v_cmp_lt_u32_e64 s[22:23], v16, v146
	v_cmp_lt_u32_e32 vcc, v17, v146
	v_or_b32_e32 v148, 8, v17
	s_cselect_b64 s[90:91], -1, 0
	v_add_f32_e32 v244, 0, v185
	s_waitcnt vmcnt(3)
	v_mfma_f32_32x32x16_f16 v[82:97], v[4:7], v[114:117], 0
	v_or_b32_e32 v5, 3, v17
	v_cmp_lt_u32_e64 s[28:29], v5, v146
	v_or_b32_e32 v4, 2, v17
	v_cmp_lt_u32_e64 s[30:31], v4, v146
	s_waitcnt vmcnt(2)
	v_mfma_f32_32x32x16_f16 v[82:97], v[8:11], v[118:121], v[82:97]
	v_lshl_add_u64 v[8:9], v[2:3], 1, s[82:83]
	v_add_co_u32_e64 v10, s[0:1], s55, v8
	global_load_dwordx2 v[158:159], v[8:9], off
	global_load_dwordx2 v[160:161], v[8:9], off offset:16
	global_load_dwordx2 v[4:5], v[8:9], off offset:32
	global_load_dwordx2 v[6:7], v[8:9], off offset:48
	v_addc_co_u32_e64 v11, s[0:1], 0, v9, s[0:1]
	s_waitcnt vmcnt(5)
	v_mfma_f32_32x32x16_f16 v[82:97], v[12:15], v[122:125], v[82:97]
	global_load_dwordx2 v[12:13], v[10:11], off
	global_load_dwordx2 v[14:15], v[10:11], off offset:16
	global_load_dwordx2 v[8:9], v[10:11], off offset:32
	s_nop 0
	global_load_dwordx2 v[10:11], v[10:11], off offset:48
	s_waitcnt vmcnt(8)
	v_mfma_f32_32x32x16_f16 v[82:97], v[216:219], v[126:129], v[82:97]
	s_branch .Lkpf_join
.Lkpf_head:
	s_mov_b32 s99, 0
	s_cmp_eq_u32 s101, 9
	s_cbranch_scc1 .Lkpf_w9
	s_waitcnt vmcnt(0)
	s_branch .Lkpf_cp
.Lkpf_w9:
	s_waitcnt vmcnt(9)
.Lkpf_cp:
	v_mov_b32_e32 v4, v82
	v_mov_b32_e32 v5, v83
	v_mov_b32_e32 v6, v84
	v_mov_b32_e32 v7, v85
	v_mov_b32_e32 v8, v86
	v_mov_b32_e32 v9, v87
	v_mov_b32_e32 v10, v88
	v_mov_b32_e32 v11, v89
	v_mov_b32_e32 v12, v90
	v_mov_b32_e32 v13, v91
	v_mov_b32_e32 v14, v92
	v_mov_b32_e32 v15, v93
	v_mov_b32_e32 v216, v94
	v_mov_b32_e32 v217, v95
	v_mov_b32_e32 v218, v96
	v_mov_b32_e32 v219, v97
	s_and_b32 s0, s23, 0xfffff000
	s_or_b32 s1, s0, s24
	v_or_b32_e32 v2, s1, v170
	v_lshlrev_b32_e32 v2, 10, v2
	v_or3_b32 v2, v2, v202, s58
	v_or_b32_e32 v2, 0x200, v2
	v_lshl_add_u64 v[16:17], v[2:3], 1, s[68:69]
	v_or_b32_e32 v2, s58, v170
	v_or_b32_e32 v17, s24, v203
	v_lshlrev_b32_e32 v2, 15, v2
	v_add3_u32 v2, v2, s0, v17
	v_or_b32_e32 v146, s95, v170
	v_or_b32_e32 v16, 1, v17
	s_cmp_lg_u32 s81, s22
	v_cmp_lt_u32_e64 s[22:23], v16, v146
	v_cmp_lt_u32_e32 vcc, v17, v146
	v_or_b32_e32 v148, 8, v17
	s_cselect_b64 s[90:91], -1, 0
	v_add_f32_e32 v244, 0, v185
	v_mfma_f32_32x32x16_f16 v[82:97], v[4:7], v[114:117], 0
	v_or_b32_e32 v5, 3, v17
	v_cmp_lt_u32_e64 s[28:29], v5, v146
	v_or_b32_e32 v4, 2, v17
	v_cmp_lt_u32_e64 s[30:31], v4, v146
	v_mfma_f32_32x32x16_f16 v[82:97], v[8:11], v[118:121], v[82:97]
	v_lshl_add_u64 v[8:9], v[2:3], 1, s[82:83]
	v_add_co_u32_e64 v10, s[0:1], s55, v8
	global_load_dwordx2 v[158:159], v[8:9], off
	global_load_dwordx2 v[160:161], v[8:9], off offset:16
	global_load_dwordx2 v[4:5], v[8:9], off offset:32
	global_load_dwordx2 v[6:7], v[8:9], off offset:48
	v_addc_co_u32_e64 v11, s[0:1], 0, v9, s[0:1]
	v_mfma_f32_32x32x16_f16 v[82:97], v[12:15], v[122:125], v[82:97]
	global_load_dwordx2 v[12:13], v[10:11], off
	global_load_dwordx2 v[14:15], v[10:11], off offset:16
	global_load_dwordx2 v[8:9], v[10:11], off offset:32
	s_nop 0
	global_load_dwordx2 v[10:11], v[10:11], off offset:48
	v_mfma_f32_32x32x16_f16 v[82:97], v[216:219], v[126:129], v[82:97]
.Lkpf_join:
	s_nop 11
	v_mul_f32_e32 v2, 0x3e000000, v82
	v_mul_f32_e32 v16, 0x3e000000, v83
	v_max_f32_e32 v197, 0, v2
	v_mul_f32_e64 v2, |v2|, s79
	v_mul_f32_e32 v149, 0x3e000000, v84
	v_max_f32_e32 v216, 0, v16
	v_mul_f32_e64 v16, |v16|, s79
	v_exp_f32_e32 v2, v2
	v_mul_f32_e32 v193, 0x3e000000, v85
	v_max_f32_e32 v217, 0, v149
	v_mul_f32_e64 v149, |v149|, s79
	v_exp_f32_e32 v16, v16
	v_mul_f32_e32 v195, 0x3e000000, v86
	v_max_f32_e32 v218, 0, v193
	v_mul_f32_e64 v193, |v193|, s79
	v_exp_f32_e32 v149, v149
	v_max_f32_e32 v219, 0, v195
	v_mul_f32_e64 v195, |v195|, s79
	v_exp_f32_e32 v193, v193
	v_mul_f32_e32 v196, 0x3e000000, v87
	v_exp_f32_e32 v195, v195
	v_add_f32_e32 v2, 1.0, v2
	v_mul_f32_e64 v215, |v196|, s79
	v_add_f32_e32 v16, 1.0, v16
	v_cmp_gt_f32_e64 s[0:1], s56, v2
	v_exp_f32_e32 v220, v215
	v_add_f32_e32 v149, 1.0, v149
	v_cndmask_b32_e64 v215, 0, 32, s[0:1]
	v_cmp_gt_f32_e64 s[24:25], s56, v16
	v_add_f32_e32 v193, 1.0, v193
	v_cmp_gt_f32_e64 s[26:27], s56, v149
	v_cndmask_b32_e64 v221, 0, 32, s[24:25]
	v_ldexp_f32 v2, v2, v215
	v_add_f32_e32 v195, 1.0, v195
	v_cndmask_b32_e64 v222, 0, 32, s[26:27]
	v_cmp_gt_f32_e64 s[34:35], s56, v193
	v_ldexp_f32 v16, v16, v221
	v_log_f32_e32 v2, v2
	v_cndmask_b32_e64 v223, 0, 32, s[34:35]
	v_cmp_gt_f32_e64 s[36:37], s56, v195
	v_ldexp_f32 v149, v149, v222
	v_log_f32_e32 v16, v16
	v_cndmask_b32_e64 v224, 0, 32, s[36:37]
	v_ldexp_f32 v193, v193, v223
	v_log_f32_e32 v149, v149
	v_ldexp_f32 v195, v195, v224
	v_log_f32_e32 v193, v193
	v_log_f32_e32 v195, v195
	v_mul_f32_e32 v225, 0x3f317217, v2
	v_mul_f32_e32 v226, 0x3f317217, v16
	v_fma_f32 v225, v2, s57, -v225
	v_mul_f32_e32 v227, 0x3f317217, v149
	v_fma_f32 v226, v16, s57, -v226
	v_fmac_f32_e32 v225, 0x3377d1cf, v2
; __device__ __forceinline__ void attn_tile(const Ctx& F, int bh, int qt, int kt, const bf16x8 (&qf)[4], f32x16& o0, f32x16& o1, float& carry) {
;     ...
;     for (int r = 0; r < 16; ++r) {
;         const float z = sT[r] * 0.125f;
;         const float sp = fmaxf(z, 0.f) + __logf(1.f + __expf(-fabsf(z)));
;         const int key = s0 + (r & 3) + 8 * (r >> 2) + 4 * hi;
;         const bool valid = !diag || (key < qpos);
;         lk[r] = valid ? -sp : 0.f;
;         lz[r] = valid ? (z - sp) : -1e30f;
;     }
	v_cndmask_b32_e64 v215, 0, v212, s[0:1]
	v_mul_f32_e32 v228, 0x3f317217, v193
	v_fma_f32 v227, v149, s57, -v227
	v_fmac_f32_e32 v226, 0x3377d1cf, v16
	v_fmac_f32_e32 v225, 0x3f317217, v2
	v_cmp_lt_f32_e64 s[0:1], |v2|, s97
	v_mul_f32_e32 v229, 0x3f317217, v195
	v_fma_f32 v228, v193, s57, -v228
	v_fmac_f32_e32 v227, 0x3377d1cf, v149
	v_fmac_f32_e32 v226, 0x3f317217, v16
	v_cndmask_b32_e64 v2, v2, v225, s[0:1]
	v_cmp_lt_f32_e64 s[0:1], |v16|, s97
	v_fma_f32 v229, v195, s57, -v229
	v_fmac_f32_e32 v228, 0x3377d1cf, v193
	v_fmac_f32_e32 v227, 0x3f317217, v149
	v_cndmask_b32_e64 v16, v16, v226, s[0:1]
	v_cmp_lt_f32_e64 s[0:1], |v149|, s97
	v_fmac_f32_e32 v229, 0x3377d1cf, v195
	v_fmac_f32_e32 v228, 0x3f317217, v193
	v_cndmask_b32_e64 v149, v149, v227, s[0:1]
	v_cmp_lt_f32_e64 s[0:1], |v193|, s97
	v_cndmask_b32_e64 v221, 0, v212, s[24:25]
	v_fmac_f32_e32 v229, 0x3f317217, v195
	v_cndmask_b32_e64 v193, v193, v228, s[0:1]
	v_cmp_lt_f32_e64 s[0:1], |v195|, s97
	v_cndmask_b32_e64 v222, 0, v212, s[26:27]
	v_cndmask_b32_e64 v224, 0, v212, s[36:37]
	v_cndmask_b32_e64 v195, v195, v229, s[0:1]
	v_sub_f32_e32 v16, v16, v221
	v_sub_f32_e32 v149, v149, v222
	v_sub_f32_e32 v222, v195, v224
	v_add_f32_e32 v195, v216, v16
	v_add_f32_e32 v16, 1.0, v220
	v_cmp_gt_f32_e64 s[0:1], s56, v16
	s_or_b64 s[26:27], vcc, s[90:91]
	s_or_b64 vcc, s[28:29], s[90:91]
	v_cmp_lt_u32_e64 s[28:29], v148, v146
	v_cndmask_b32_e64 v148, 0, 32, s[0:1]
	v_ldexp_f32 v16, v16, v148
	v_log_f32_e32 v16, v16
	v_sub_f32_e32 v2, v2, v215
	v_add_f32_e32 v215, v197, v2
	s_or_b64 s[24:25], s[22:23], s[90:91]
	v_mul_f32_e32 v197, 0x3f317217, v16
	v_fma_f32 v197, v16, s57, -v197
	v_fmac_f32_e32 v197, 0x3377d1cf, v16
	s_or_b64 s[22:23], s[30:31], s[90:91]
	v_fmac_f32_e32 v197, 0x3f317217, v16
	v_cmp_lt_f32_e64 s[30:31], |v16|, s97
	v_max_f32_e32 v196, 0, v196
	v_add_f32_e32 v219, v219, v222
	v_cndmask_b32_e64 v16, v16, v197, s[30:31]
	v_cndmask_b32_e64 v197, 0, v212, s[0:1]
	v_sub_f32_e32 v16, v16, v197
	v_mul_f32_e32 v197, 0x3e000000, v88
	v_mul_f32_e64 v220, |v197|, s79
	v_exp_f32_e32 v220, v220
	v_add_f32_e32 v222, v196, v16
	v_or_b32_e32 v16, 9, v17
	v_cmp_lt_u32_e64 s[0:1], v16, v146
	v_add_f32_e32 v16, 1.0, v220
	v_cndmask_b32_e64 v223, 0, v212, s[34:35]
	v_cmp_gt_f32_e64 s[34:35], s56, v16
	s_or_b64 s[30:31], s[0:1], s[90:91]
	v_sub_f32_e32 v221, v193, v223
	v_cndmask_b32_e64 v196, 0, 32, s[34:35]
	v_ldexp_f32 v16, v16, v196
	v_log_f32_e32 v196, v16
	v_add_f32_e32 v2, v218, v221
	v_max_f32_e32 v197, 0, v197
	v_add_f32_e32 v193, v217, v149
	v_mul_f32_e32 v220, 0x3f317217, v196
	v_fma_f32 v220, v196, s57, -v220
	v_fmac_f32_e32 v220, 0x3377d1cf, v196
	v_fmac_f32_e32 v220, 0x3f317217, v196
	v_cmp_lt_f32_e64 s[0:1], |v196|, s97
	v_cndmask_b32_e64 v149, 0, -v215, s[26:27]
	v_cndmask_b32_e64 v216, 0, -v195, s[24:25]
	v_cndmask_b32_e64 v196, v196, v220, s[0:1]
	v_cndmask_b32_e64 v220, 0, v212, s[34:35]
	v_sub_f32_e32 v196, v196, v220
	v_mul_f32_e32 v220, 0x3e000000, v89
	v_mul_f32_e64 v221, |v220|, s79
	v_exp_f32_e32 v221, v221
	v_add_f32_e32 v223, v197, v196
	v_or_b32_e32 v196, 10, v17
	v_cmp_lt_u32_e64 s[0:1], v196, v146
	v_add_f32_e32 v196, 1.0, v221
	v_cmp_gt_f32_e64 s[36:37], s56, v196
	s_or_b64 s[34:35], s[0:1], s[90:91]
	v_max_f32_e32 v220, 0, v220
	v_cndmask_b32_e64 v197, 0, 32, s[36:37]
	v_ldexp_f32 v196, v196, v197
	v_log_f32_e32 v197, v196
	v_cndmask_b32_e64 v225, 0, v212, s[36:37]
	v_cndmask_b32_e64 v217, 0, -v193, s[22:23]
	v_cndmask_b32_e64 v218, 0, -v2, vcc
	v_mul_f32_e32 v221, 0x3f317217, v197
	v_fma_f32 v221, v197, s57, -v221
	v_fmac_f32_e32 v221, 0x3377d1cf, v197
	v_fmac_f32_e32 v221, 0x3f317217, v197
	v_cmp_lt_f32_e64 s[0:1], |v197|, s97
	s_or_b64 s[28:29], s[28:29], s[90:91]
	v_cndmask_b32_e64 v148, 0, -v219, s[28:29]
	v_cndmask_b32_e64 v197, v197, v221, s[0:1]
	v_mul_f32_e32 v221, 0x3e000000, v90
	v_mul_f32_e64 v224, |v221|, s79
	v_exp_f32_e32 v224, v224
	v_sub_f32_e32 v197, v197, v225
	v_add_f32_e32 v225, v220, v197
	v_cndmask_b32_e64 v16, 0, -v222, s[30:31]
	v_add_f32_e32 v197, 1.0, v224
	v_cmp_gt_f32_e64 s[0:1], s56, v197
	v_cndmask_b32_e64 v196, 0, -v223, s[34:35]
	v_fma_f32 v86, v86, s78, -v219
	v_cndmask_b32_e64 v220, 0, 32, s[0:1]
	v_ldexp_f32 v197, v197, v220
	v_log_f32_e32 v197, v197
	v_or_b32_e32 v220, 11, v17
	v_cmp_lt_u32_e64 s[36:37], v220, v146
	v_max_f32_e32 v220, 0, v221
	v_mul_f32_e32 v221, 0x3f317217, v197
	v_fma_f32 v221, v197, s57, -v221
	v_fmac_f32_e32 v221, 0x3377d1cf, v197
	v_fmac_f32_e32 v221, 0x3f317217, v197
	v_cmp_lt_f32_e64 s[38:39], |v197|, s97
	v_cndmask_b32_e64 v86, v214, v86, s[28:29]
	v_fma_f32 v82, v82, s78, -v215
	v_cndmask_b32_e64 v197, v197, v221, s[38:39]
	v_cndmask_b32_e64 v221, 0, v212, s[0:1]
	v_sub_f32_e32 v197, v197, v221
	v_mul_f32_e32 v221, 0x3e000000, v91
	v_mul_f32_e64 v224, |v221|, s79
	v_exp_f32_e32 v224, v224
	v_add_f32_e32 v226, v220, v197
	v_or_b32_e32 v197, 16, v17
	v_cmp_lt_u32_e64 s[0:1], v197, v146
	v_add_f32_e32 v197, 1.0, v224
	v_cmp_gt_f32_e64 s[40:41], s56, v197
	s_or_b64 s[38:39], s[0:1], s[90:91]
	v_max_f32_e32 v221, 0, v221
	v_cndmask_b32_e64 v220, 0, 32, s[40:41]
	v_ldexp_f32 v197, v197, v220
	v_log_f32_e32 v197, v197
	v_cndmask_b32_e64 v220, 0, -v226, s[38:39]
	v_fma_f32 v90, v90, s78, -v226
	v_cndmask_b32_e64 v226, v214, v90, s[38:39]
	v_mul_f32_e32 v224, 0x3f317217, v197
	v_fma_f32 v224, v197, s57, -v224
	v_fmac_f32_e32 v224, 0x3377d1cf, v197
	v_fmac_f32_e32 v224, 0x3f317217, v197
	v_cmp_lt_f32_e64 s[0:1], |v197|, s97
	v_fma_f32 v83, v83, s78, -v195
	v_fma_f32 v84, v84, s78, -v193
	v_cndmask_b32_e64 v197, v197, v224, s[0:1]
	v_cndmask_b32_e64 v224, 0, v212, s[40:41]
	v_sub_f32_e32 v197, v197, v224
; __device__ __forceinline__ void attn_tile(const Ctx& F, int bh, int qt, int kt, const bf16x8 (&qf)[4], f32x16& o0, f32x16& o1, float& carry) {
;     ...
;     for (int r = 0; r < 16; ++r) {
;         const float z = sT[r] * 0.125f;
;         const float sp = fmaxf(z, 0.f) + __logf(1.f + __expf(-fabsf(z)));
;         const int key = s0 + (r & 3) + 8 * (r >> 2) + 4 * hi;
;         const bool valid = !diag || (key < qpos);
;         lk[r] = valid ? -sp : 0.f;
;         lz[r] = valid ? (z - sp) : -1e30f;
;     }
;     float g[4], pg[4];
; #pragma unroll
;     for (int q = 0; q < 4; ++q) { g[q] = (lk[4 * q] + lk[4 * q + 1]) + (lk[4 * q + 2] + lk[4 * q + 3]); pg[q] = __shfl_xor(g[q], 32); }
	v_mul_f32_e32 v224, 0x3e000000, v92
	v_mul_f32_e64 v227, |v224|, s79
	v_exp_f32_e32 v227, v227
	v_add_f32_e32 v228, v221, v197
	v_or_b32_e32 v197, 17, v17
	v_cmp_lt_u32_e64 s[0:1], v197, v146
	v_add_f32_e32 v197, 1.0, v227
	v_cmp_gt_f32_e64 s[40:41], s56, v197
	s_or_b64 s[42:43], s[0:1], s[90:91]
	v_cndmask_b32_e64 v227, 0, -v228, s[42:43]
	v_cndmask_b32_e64 v221, 0, 32, s[40:41]
	v_ldexp_f32 v197, v197, v221
	v_log_f32_e32 v197, v197
	v_max_f32_e32 v221, 0, v224
	v_fma_f32 v90, v91, s78, -v228
	v_cndmask_b32_e64 v228, v214, v90, s[42:43]
	v_mul_f32_e32 v224, 0x3f317217, v197
	v_fma_f32 v224, v197, s57, -v224
	v_fmac_f32_e32 v224, 0x3377d1cf, v197
	v_fmac_f32_e32 v224, 0x3f317217, v197
	v_cmp_lt_f32_e64 s[0:1], |v197|, s97
	v_fma_f32 v2, v85, s78, -v2
	v_cndmask_b32_e64 v82, v214, v82, s[26:27]
	v_cndmask_b32_e64 v197, v197, v224, s[0:1]
	v_cndmask_b32_e64 v224, 0, v212, s[40:41]
	v_sub_f32_e32 v197, v197, v224
	v_mul_f32_e32 v224, 0x3e000000, v93
	v_mul_f32_e64 v229, |v224|, s79
	v_exp_f32_e32 v229, v229
	v_add_f32_e32 v230, v221, v197
	v_or_b32_e32 v197, 18, v17
	v_cmp_lt_u32_e64 s[0:1], v197, v146
	v_add_f32_e32 v197, 1.0, v229
	v_cmp_gt_f32_e64 s[40:41], s56, v197
	s_or_b64 s[46:47], s[0:1], s[90:91]
	v_cndmask_b32_e64 v229, 0, -v230, s[46:47]
	v_cndmask_b32_e64 v221, 0, 32, s[40:41]
	v_ldexp_f32 v197, v197, v221
	v_log_f32_e32 v197, v197
	v_max_f32_e32 v221, 0, v224
	v_fma_f32 v90, v92, s78, -v230
	v_cndmask_b32_e64 v92, v214, v90, s[46:47]
	v_mul_f32_e32 v224, 0x3f317217, v197
	v_fma_f32 v224, v197, s57, -v224
	v_fmac_f32_e32 v224, 0x3377d1cf, v197
	v_fmac_f32_e32 v224, 0x3f317217, v197
	v_cmp_lt_f32_e64 s[0:1], |v197|, s97
	v_cndmask_b32_e64 v83, v214, v83, s[24:25]
	v_cndmask_b32_e64 v84, v214, v84, s[22:23]
	v_cndmask_b32_e64 v197, v197, v224, s[0:1]
	v_cndmask_b32_e64 v224, 0, v212, s[40:41]
	v_sub_f32_e32 v197, v197, v224
	v_mul_f32_e32 v224, 0x3e000000, v94
	v_mul_f32_e64 v231, |v224|, s79
	v_exp_f32_e32 v231, v231
	v_add_f32_e32 v232, v221, v197
	v_or_b32_e32 v197, 19, v17
	v_cmp_lt_u32_e64 s[0:1], v197, v146
	v_add_f32_e32 v197, 1.0, v231
	v_cmp_gt_f32_e64 s[40:41], s56, v197
	s_or_b64 s[48:49], s[0:1], s[90:91]
	v_cndmask_b32_e64 v231, 0, -v232, s[48:49]
	v_cndmask_b32_e64 v221, 0, 32, s[40:41]
	v_ldexp_f32 v197, v197, v221
	v_log_f32_e32 v197, v197
	v_max_f32_e32 v221, 0, v224
	v_cndmask_b32_e32 v2, v214, v2, vcc
	v_mul_f32_e32 v224, 0x3f317217, v197
	v_fma_f32 v224, v197, s57, -v224
	v_fmac_f32_e32 v224, 0x3377d1cf, v197
	v_fmac_f32_e32 v224, 0x3f317217, v197
	v_cmp_lt_f32_e64 s[0:1], |v197|, s97
	s_nop 1
	v_cndmask_b32_e64 v197, v197, v224, s[0:1]
	v_cndmask_b32_e64 v224, 0, v212, s[40:41]
	v_sub_f32_e32 v197, v197, v224
	v_mul_f32_e32 v224, 0x3e000000, v95
	v_mul_f32_e64 v233, |v224|, s79
	v_exp_f32_e32 v233, v233
	v_add_f32_e32 v234, v221, v197
	v_or_b32_e32 v197, 24, v17
	v_cmp_lt_u32_e64 s[0:1], v197, v146
	v_add_f32_e32 v197, 1.0, v233
	v_cmp_gt_f32_e64 s[44:45], s56, v197
	s_or_b64 s[40:41], s[0:1], s[90:91]
	v_cndmask_b32_e64 v233, 0, -v234, s[40:41]
	v_cndmask_b32_e64 v221, 0, 32, s[44:45]
	v_ldexp_f32 v197, v197, v221
	v_log_f32_e32 v197, v197
	v_max_f32_e32 v221, 0, v224
	v_mul_f32_e32 v224, 0x3f317217, v197
	v_fma_f32 v224, v197, s57, -v224
	v_fmac_f32_e32 v224, 0x3377d1cf, v197
	v_fmac_f32_e32 v224, 0x3f317217, v197
	v_cmp_lt_f32_e64 s[0:1], |v197|, s97
	s_nop 1
	v_cndmask_b32_e64 v197, v197, v224, s[0:1]
	v_cndmask_b32_e64 v224, 0, v212, s[44:45]
	v_sub_f32_e32 v197, v197, v224
	v_mul_f32_e32 v224, 0x3e000000, v96
	v_mul_f32_e64 v235, |v224|, s79
	v_exp_f32_e32 v235, v235
	v_add_f32_e32 v236, v221, v197
	v_or_b32_e32 v197, 25, v17
	v_cmp_lt_u32_e64 s[0:1], v197, v146
	v_add_f32_e32 v197, 1.0, v235
	v_cmp_gt_f32_e64 s[50:51], s56, v197
	s_or_b64 s[44:45], s[0:1], s[90:91]
	v_cndmask_b32_e64 v235, 0, -v236, s[44:45]
	v_cndmask_b32_e64 v221, 0, 32, s[50:51]
	v_ldexp_f32 v197, v197, v221
	v_log_f32_e32 v197, v197
	v_max_f32_e32 v221, 0, v224
	v_mul_f32_e32 v224, 0x3f317217, v197
	v_fma_f32 v224, v197, s57, -v224
	v_fmac_f32_e32 v224, 0x3377d1cf, v197
	v_fmac_f32_e32 v224, 0x3f317217, v197
	v_cmp_lt_f32_e64 s[0:1], |v197|, s97
	s_nop 1
	v_cndmask_b32_e64 v197, v197, v224, s[0:1]
	v_cndmask_b32_e64 v224, 0, v212, s[50:51]
	v_sub_f32_e32 v197, v197, v224
	v_mul_f32_e32 v224, 0x3e000000, v97
	v_mul_f32_e64 v237, |v224|, s79
	v_exp_f32_e32 v237, v237
	v_add_f32_e32 v238, v221, v197
	v_or_b32_e32 v197, 26, v17
	v_cmp_lt_u32_e64 s[0:1], v197, v146
	v_add_f32_e32 v197, 1.0, v237
	v_cmp_gt_f32_e64 s[52:53], s56, v197
	s_or_b64 s[50:51], s[0:1], s[90:91]
	v_or_b32_e32 v17, 27, v17
	v_cndmask_b32_e64 v221, 0, 32, s[52:53]
	v_ldexp_f32 v197, v197, v221
	v_log_f32_e32 v197, v197
	v_max_f32_e32 v221, 0, v224
	v_cndmask_b32_e64 v237, 0, -v238, s[50:51]
	v_mul_f32_e32 v224, 0x3f317217, v197
	v_fma_f32 v224, v197, s57, -v224
	v_fmac_f32_e32 v224, 0x3377d1cf, v197
	v_fmac_f32_e32 v224, 0x3f317217, v197
	v_cmp_lt_f32_e64 s[0:1], |v197|, s97
	s_nop 1
	v_cndmask_b32_e64 v197, v197, v224, s[0:1]
	v_cmp_lt_u32_e64 s[0:1], v17, v146
	v_and_b32_e32 v146, 64, v213
	v_xor_b32_e32 v17, 32, v213
	v_add_u32_e32 v146, 64, v146
	v_cndmask_b32_e64 v224, 0, v212, s[52:53]
	s_or_b64 s[52:53], s[0:1], s[90:91]
	v_cmp_lt_i32_e64 s[0:1], v17, v146
	v_sub_f32_e32 v197, v197, v224
	v_add_f32_e32 v224, v221, v197
	v_cndmask_b32_e64 v17, v213, v17, s[0:1]
	v_lshlrev_b32_e32 v146, 2, v17
	v_add_f32_e32 v17, v149, v216
	v_add_f32_e32 v149, v217, v218
	v_cndmask_b32_e64 v239, 0, -v224, s[52:53]
	v_add_f32_e32 v240, v17, v149
	v_add_f32_e32 v17, v220, v227
	v_add_f32_e32 v149, v229, v231
	v_add_f32_e32 v197, v17, v149
	v_add_f32_e32 v17, v233, v235
	v_add_f32_e32 v149, v237, v239
	v_add_f32_e32 v149, v17, v149
	ds_bpermute_b32 v221, v146, v197
	ds_bpermute_b32 v17, v146, v149
	s_or_b64 s[0:1], s[36:37], s[90:91]
	v_cndmask_b32_e64 v220, 0, -v225, s[0:1]
	ds_bpermute_b32 v241, v146, v240
	s_waitcnt lgkmcnt(2)
; #define MFMA32(a, b, c) __builtin_amdgcn_mfma_f32_32x32x16_f16(H8(a), H8(b), (c), 0, 0, 0)
; __device__ __forceinline__ void attn_tile(const Ctx& F, int bh, int qt, int kt, const bf16x8 (&qf)[4], f32x16& o0, f32x16& o1, float& carry) {
;     ...
;     float Tq[4]; Tq[3] = 0.f; Tq[2] = g[3] + pg[3]; Tq[1] = Tq[2] + (g[2] + pg[2]); Tq[0] = Tq[1] + (g[1] + pg[1]);
;     const float total = Tq[0] + (g[0] + pg[0]);
;     float w[16];
; #pragma unroll
;     for (int q = 0; q < 4; ++q) {
;         const float after = carry + Tq[q] + (hi == 0 ? pg[q] : 0.f);
;         const float l3 = after, l2 = l3 + lk[4 * q + 3], l1 = l2 + lk[4 * q + 2], l0 = l1 + lk[4 * q + 1];
;         w[4 * q + 3] = __expf(lz[4 * q + 3] + l3); w[4 * q + 2] = __expf(lz[4 * q + 2] + l2);
;         w[4 * q + 1] = __expf(lz[4 * q + 1] + l1); w[4 * q + 0] = __expf(lz[4 * q + 0] + l0);
;     }
;     carry += total;
;     bf16x8 pw[2];
; #pragma unroll
;     for (int s = 0; s < 2; ++s) { u32x4 t; t.x = pk2(w[8 * s], w[8 * s + 1]); t.y = pk2(w[8 * s + 2], w[8 * s + 3]); t.z = pk2(w[8 * s + 4], w[8 * s + 5]); t.w = pk2(w[8 * s + 6], w[8 * s + 7]); pw[s] = __builtin_bit_cast(bf16x8, t); }
; #pragma unroll
;     for (int s = 0; s < 2; ++s) { o0 = MFMA32(vf[0][s], pw[s], o0); o1 = MFMA32(vf[1][s], pw[s], o1); }
; }
; __device__ __forceinline__ void attn_fin(const Ctx& F, const float* sbg, int bh, int qt, const f32x16& o0, const f32x16& o1) {
;     const int lane = F.lane, j = lane & 31, hi = lane >> 5; const int b = bh >> 3, h = bh & 7;
;     bf16* CAT = (bf16*)(F.ws + WS_CAT);
;     float ss = 0.f;
; #pragma unroll
;     for (int r = 0; r < 16; ++r) ss += o0[r] * o0[r] + o1[r] * o1[r];
;     ss += __shfl_xor(ss, 32);
;     const float rstd = rsqrtf(ss * (1.f / 64.f) + NORM_EPS);
;     const float* sg = sbg + h * 64;
;     bf16* orow = CAT + ((size_t)b * SEQ + qt * 32 + j) * 1024 + h * 64;
; #pragma unroll
;     for (int q = 0; q < 4; ++q) { const int d = 8 * q + 4 * hi; const f32x4 g0 = *(const f32x4*)(sg + d), g1 = *(const f32x4*)(sg + 32 + d);
;         u32x2 t; t.x = pk2(o0[4 * q] * rstd * g0.x, o0[4 * q + 1] * rstd * g0.y); t.y = pk2(o0[4 * q + 2] * rstd * g0.z, o0[4 * q + 3] * rstd * g0.w); *(u32x2*)(orow + d) = t;
;         t.x = pk2(o1[4 * q] * rstd * g1.x, o1[4 * q + 1] * rstd * g1.y); t.y = pk2(o1[4 * q + 2] * rstd * g1.z, o1[4 * q + 3] * rstd * g1.w); *(u32x2*)(orow + 32 + d) = t; }
; }
	v_cndmask_b32_e64 v242, 0, v221, s[20:21]
	s_waitcnt lgkmcnt(1)
	v_pk_add_f32 v[90:91], v[148:149], v[16:17]
	v_pk_add_f32 v[148:149], v[196:197], v[220:221]
	v_cndmask_b32_e64 v243, 0, v17, s[20:21]
	v_pk_add_f32 v[148:149], v[90:91], v[148:149]
	ds_bpermute_b32 v17, v146, v148
	v_fma_f32 v90, v93, s78, -v232
	v_add_f32_e32 v91, v185, v91
	v_cndmask_b32_e64 v90, v214, v90, s[48:49]
	v_add_f32_e32 v91, v242, v91
	s_waitcnt lgkmcnt(0)
	v_cndmask_b32_e64 v93, 0, v17, s[20:21]
	v_add_f32_e32 v197, v231, v91
	v_add_f32_e32 v90, v90, v91
	v_add_f32_e32 v91, v185, v149
	v_add_f32_e32 v91, v93, v91
	v_add_f32_e32 v93, v220, v91
	v_add_f32_e32 v196, v196, v93
	v_add_f32_e32 v17, v148, v17
	v_add_f32_e32 v16, v16, v196
	v_add_f32_e32 v17, v17, v149
	v_cndmask_b32_e64 v233, 0, v241, s[20:21]
	v_add_f32_e32 v16, v86, v16
	v_fma_f32 v86, v87, s78, -v222
	v_fma_f32 v87, v88, s78, -v223
	v_fma_f32 v88, v89, s78, -v225
	v_add_f32_e32 v89, v185, v17
	v_cndmask_b32_e64 v88, v214, v88, s[0:1]
	v_add_f32_e32 v89, v233, v89
	v_cndmask_b32_e64 v87, v214, v87, s[34:35]
	v_add_f32_e32 v88, v88, v91
	v_add_f32_e32 v91, v218, v89
	v_add_f32_e32 v87, v87, v93
	v_add_f32_e32 v93, v217, v91
	v_cndmask_b32_e64 v86, v214, v86, s[30:31]
	v_add_f32_e32 v148, v216, v93
	v_add_f32_e32 v86, v86, v196
	v_add_f32_e32 v82, v82, v148
	v_add_f32_e32 v83, v83, v93
	v_add_f32_e32 v84, v84, v91
	v_add_f32_e32 v2, v2, v89
	v_mul_f32_e32 v16, 0x3fb8aa3b, v16
	v_mul_f32_e32 v86, 0x3fb8aa3b, v86
	v_mul_f32_e32 v87, 0x3fb8aa3b, v87
	v_mul_f32_e32 v88, 0x3fb8aa3b, v88
	v_mul_f32_e32 v82, 0x3fb8aa3b, v82
	v_mul_f32_e32 v83, 0x3fb8aa3b, v83
	v_mul_f32_e32 v84, 0x3fb8aa3b, v84
	v_mul_f32_e32 v2, 0x3fb8aa3b, v2
	v_exp_f32_e32 v16, v16
	v_exp_f32_e32 v86, v86
	v_exp_f32_e32 v87, v87
	v_exp_f32_e32 v88, v88
	v_exp_f32_e32 v82, v82
	v_exp_f32_e32 v83, v83
	v_exp_f32_e32 v84, v84
	v_exp_f32_e32 v2, v2
	v_fma_f32 v85, v97, s78, -v224
	v_cndmask_b32_e64 v85, v214, v85, s[52:53]
	v_fma_f32 v93, v94, s78, -v234
	v_add_f32_e32 v94, v244, v243
	v_fma_f32 v91, v95, s78, -v236
	v_add_f32_e32 v95, v239, v94
	v_add_f32_e32 v85, v94, v85
	v_add_f32_e32 v219, v229, v197
	v_fma_f32 v89, v96, s78, -v238
	v_add_f32_e32 v96, v237, v95
	v_mul_f32_e32 v94, 0x3fb8aa3b, v85
	v_cvt_pk_f16_f32 v82, v82, v83
	v_cvt_pk_f16_f32 v83, v84, v2
	v_cvt_pk_f16_f32 v84, v16, v86
	v_cvt_pk_f16_f32 v85, v87, v88
	v_add_f32_e32 v221, v227, v219
	v_cndmask_b32_e64 v89, v214, v89, s[50:51]
	v_cndmask_b32_e64 v91, v214, v91, s[44:45]
	v_cndmask_b32_e64 v93, v214, v93, s[40:41]
	v_add_f32_e32 v97, v235, v96
	s_waitcnt vmcnt(6)
	v_mfma_f32_32x32x16_f16 v[66:81], v[158:161], v[82:85], v[66:81]
	v_add_f32_e32 v221, v226, v221
	v_add_f32_e32 v219, v228, v219
	v_add_f32_e32 v92, v92, v197
	v_add_f32_e32 v16, v89, v95
	v_add_f32_e32 v86, v91, v96
	v_add_f32_e32 v87, v93, v97
	v_mul_f32_e32 v221, 0x3fb8aa3b, v221
	s_waitcnt vmcnt(2)
	v_mfma_f32_32x32x16_f16 v[50:65], v[12:15], v[82:85], v[50:65]
	v_mul_f32_e32 v219, 0x3fb8aa3b, v219
	v_mul_f32_e32 v92, 0x3fb8aa3b, v92
	v_mul_f32_e32 v90, 0x3fb8aa3b, v90
	v_mul_f32_e32 v16, 0x3fb8aa3b, v16
	v_mul_f32_e32 v86, 0x3fb8aa3b, v86
	v_mul_f32_e32 v12, 0x3fb8aa3b, v87
	v_exp_f32_e32 v221, v221
	v_exp_f32_e32 v219, v219
	v_exp_f32_e32 v92, v92
	v_exp_f32_e32 v90, v90
	v_exp_f32_e32 v2, v94
	v_exp_f32_e32 v86, v86
	v_exp_f32_e32 v14, v12
	v_exp_f32_e32 v15, v16
	v_cvt_pk_f16_f32 v12, v221, v219
	v_cvt_pk_f16_f32 v13, v92, v90
	v_cvt_pk_f16_f32 v14, v14, v86
	v_cvt_pk_f16_f32 v15, v15, v2
	v_add_f32_e32 v2, v240, v241
	s_cmp_eq_u32 s81, 0
	v_mfma_f32_32x32x16_f16 v[66:81], v[4:7], v[12:15], v[66:81]
	v_add_f32_e32 v2, v2, v17
	s_cselect_b64 s[0:1], -1, 0
	v_add_f32_e32 v185, v185, v2
	s_and_b64 vcc, exec, s[0:1]
	s_waitcnt vmcnt(0)
	v_mfma_f32_32x32x16_f16 v[50:65], v[8:11], v[12:15], v[50:65]
	s_cbranch_vccnz .LBB0_675
	s_add_i32 s81, s81, -1
	v_cmp_gt_f32_e32 vcc, s76, v185
	s_cmp_eq_u64 vcc, exec
	s_cselect_b64 s[0:1], -1, 0
	s_andn2_b64 vcc, exec, s[0:1]
	s_cbranch_vccz .LBB0_676
	s_ashr_i32 s0, s92, 7
	s_lshl_b32 s1, s0, 9
	s_and_b32 s1, s1, 0xfffff000
	s_lshl_b32 s100, s81, 5
	s_or_b32 s1, s1, s100
	s_lshl_b32 s0, s0, 6
	s_and_b32 s0, s0, 0x1c0
	v_or_b32_e32 v220, s1, v170
	v_lshlrev_b32_e32 v220, 10, v220
	v_or3_b32 v220, v220, v202, s0
	v_or_b32_e32 v220, 0x200, v220
	v_mov_b32_e32 v221, 0
	v_lshl_add_u64 v[220:221], v[220:221], 1, s[68:69]
	s_mov_b32 s99, 1
	s_branch .LBB0_677

; #define H_ISSUE(ch_) do { _Pragma("unroll") for (int a_ = 0; a_ < 6; ++a_) st[a_] = *(const u32x4*)(sbase + (size_t)a_ * SCAN_ARR + (size_t)(ch_) * (T * 64 * 2)); \
;         krv = scal[((ch_) * T + stp) * 2]; } while (0)
; #define H_FLUSH(ch_) do { const LAS float* yb_ = ybufs + ((ch_) & 1) * (T * 16); \
;         _Pragma("unroll") for (int i_ = 0; i_ < 2; ++i_) { const int idx_ = ht + 256 * i_; Y[(size_t)((ch_) * T + (idx_ >> 4)) * 64 + qtr * 16 + (idx_ & 15)] = yb_[idx_]; } } while (0)
; __device__ __forceinline__ void scan_phase(const Ctx& F, const float* sbg) {
;     ...
;             for (int ch = 0; ch < NCH; ++ch) {
;                 if (ch + 1 < NCH) { H_COMMIT((ch + 1) & 1); if (ch + 2 < NCH) H_ISSUE(ch + 2); }
;                 if (ch > 0) H_FLUSH(ch - 1);
;                 ATTN_STEP(F.G * 4);
;                 asm volatile("s_waitcnt lgkmcnt(0)\n\ts_barrier" ::: "memory");
;             }
;             H_FLUSH(NCH - 1);
;             while (au < 64 * 128) ATTN_STEP(F.G * 4);
.LBB0_677:
	s_cmp_eq_u32 s99, 1
	s_cbranch_scc1 .Lkpf_issue
	v_mov_b32_e32 v220, s68
	v_mov_b32_e32 v221, s69
.Lkpf_issue:
	global_load_dwordx4 v[82:85], v[220:221], off
	global_load_dwordx4 v[86:89], v[220:221], off offset:32
	global_load_dwordx4 v[90:93], v[220:221], off offset:64
	global_load_dwordx4 v[94:97], v[220:221], off offset:96
	s_mov_b32 s101, 0
	s_addk_i32 s96, 0x200
	s_waitcnt lgkmcnt(0)
	s_barrier
	s_add_u32 s88, s88, 0x1000
	s_mov_b64 s[0:1], 0x2000
	s_addc_u32 s89, s89, 0
	v_add_u32_e32 v194, 32, v194
	v_lshl_add_u64 v[188:189], v[188:189], 0, s[0:1]
	s_cmp_eq_u32 s88, 0x80000
	v_add_u32_e32 v192, 64, v192
	s_cbranch_scc1 .LBB0_679
	s_mov_b32 s26, s94
	s_add_i32 s94, s26, 1
	s_cmp_eq_u32 s88, 0x7f000
	s_cbranch_scc0 .LBB0_664
	s_branch .LBB0_666
.LBB0_679:
	s_waitcnt vmcnt(0)
	ds_read_b32 v2, v204
	ds_read_b32 v8, v205
	v_lshl_add_u64 v[4:5], v[186:187], 0, v[174:175]
	v_lshl_add_u64 v[6:7], v[186:187], 0, v[176:177]
	s_cmpk_lt_i32 s92, 0x2000
	s_waitcnt lgkmcnt(1)
	global_store_dword v[4:5], v2, off
	v_add_co_u32_e32 v4, vcc, 0xfe000, v6
	s_nop 1
	v_addc_co_u32_e32 v5, vcc, 0, v7, vcc
	s_waitcnt lgkmcnt(0)
	global_store_dword v[4:5], v8, off
	s_cbranch_scc0 .LBB0_690
	v_and_b32_e32 v4, 64, v213
	v_xor_b32_e32 v2, 32, v213
	v_add_u32_e32 v4, 64, v4
	v_cmp_lt_i32_e32 vcc, v2, v4
	s_nop 1
	v_cndmask_b32_e32 v2, v213, v2, vcc
	s_waitcnt vmcnt(6)
	v_lshlrev_b32_e32 v138, 2, v2
	s_branch .LBB0_682
